# row-sum xor-16/xor-32 shuffles in the out-proj and FFN-out epilogues: ds_bpermute round trips replaced by v_permlane16/32_swap on a copy
# speedup vs baseline: 1.0019x; 1.0019x over previous
.LBB0_518:
	v_lshl_or_b32 v190, s26, 8, v189
	v_lshl_add_u32 v198, s28, 8, v1
	v_ashrrev_i32_e32 v191, 31, v190
	v_ashrrev_i32_e32 v199, 31, v198
	v_lshlrev_b64 v[228:229], 1, v[190:191]
	v_lshl_add_u64 v[200:201], s[40:41], 0, v[228:229]
	v_lshlrev_b64 v[146:147], 11, v[198:199]
	v_lshl_add_u64 v[82:83], v[200:201], 0, v[146:147]
	global_load_dwordx4 v[220:223], v[82:83], off
	global_load_dwordx4 v[224:227], v[82:83], off offset:256
	v_lshl_add_u64 v[82:83], v[190:191], 2, s[12:13]
	v_lshl_add_u64 v[148:149], v[198:199], 2, s[8:9]
	global_load_dwordx4 v[102:105], v[82:83], off
	global_load_dwordx4 v[98:101], v[82:83], off offset:16
	global_load_dwordx4 v[86:89], v[82:83], off offset:512
	s_nop 0
	global_load_dwordx4 v[82:85], v[82:83], off offset:528
	v_or_b32_e32 v212, 16, v198
	global_load_dword v230, v[148:149], off
	v_or_b32_e32 v206, 32, v198
	v_or_b32_e32 v202, 48, v198
	v_ashrrev_i32_e32 v213, 31, v212
	v_ashrrev_i32_e32 v207, 31, v206
	v_ashrrev_i32_e32 v203, 31, v202
	v_lshlrev_b64 v[218:219], 11, v[212:213]
	v_lshlrev_b64 v[214:215], 11, v[206:207]
	global_load_dword v216, v[148:149], off offset:64
	global_load_dword v210, v[148:149], off offset:128
	global_load_dword v204, v[148:149], off offset:192
	global_load_dword v196, v[148:149], off offset:512
	global_load_dword v194, v[148:149], off offset:576
	global_load_dword v192, v[148:149], off offset:640
	global_load_dword v188, v[148:149], off offset:704
	v_lshlrev_b64 v[208:209], 11, v[202:203]
	v_lshl_add_u64 v[232:233], s[40:41], 0, v[146:147]
	v_lshl_add_u64 v[146:147], v[200:201], 0, v[218:219]
	v_lshl_add_u64 v[148:149], v[200:201], 0, v[214:215]
	v_lshl_add_u64 v[234:235], v[200:201], 0, v[208:209]
	global_load_dwordx4 v[166:169], v[146:147], off
	global_load_dwordx4 v[162:165], v[146:147], off offset:256
	global_load_dwordx4 v[158:161], v[148:149], off
	global_load_dwordx4 v[154:157], v[148:149], off offset:256
	global_load_dwordx4 v[150:153], v[234:235], off
	s_nop 0
	global_load_dwordx4 v[146:149], v[234:235], off offset:256
	v_lshl_add_u64 v[228:229], v[232:233], 0, v[228:229]
	s_waitcnt vmcnt(0)
	v_lshlrev_b32_e32 v232, 16, v220
	v_and_b32_e32 v233, 0xffff0000, v220
	v_lshlrev_b32_e32 v220, 16, v221
	v_and_b32_e32 v221, 0xffff0000, v221
	v_lshlrev_b32_e32 v234, 16, v222
	v_and_b32_e32 v235, 0xffff0000, v222
	v_lshlrev_b32_e32 v236, 16, v224
	v_and_b32_e32 v237, 0xffff0000, v224
	v_lshlrev_b32_e32 v224, 16, v225
	v_and_b32_e32 v225, 0xffff0000, v225
	v_lshlrev_b32_e32 v238, 16, v226
	v_and_b32_e32 v239, 0xffff0000, v226
	v_pk_mul_f32 v[232:233], v[102:103], v[232:233]
	v_pk_mul_f32 v[220:221], v[104:105], v[220:221]
	v_pk_mul_f32 v[234:235], v[98:99], v[234:235]
	v_pk_mul_f32 v[224:225], v[88:89], v[224:225]
	v_pk_mul_f32 v[238:239], v[82:83], v[238:239]
	v_pk_fma_f32 v[144:145], v[230:231], v[220:221], v[144:145] op_sel_hi:[0,1,1]
	v_pk_fma_f32 v[142:143], v[230:231], v[232:233], v[142:143] op_sel_hi:[0,1,1]
	v_lshlrev_b32_e32 v222, 16, v223
	v_and_b32_e32 v223, 0xffff0000, v223
	v_lshlrev_b32_e32 v226, 16, v227
	v_and_b32_e32 v227, 0xffff0000, v227
	v_pk_mul_f32 v[236:237], v[86:87], v[236:237]
	v_pk_fma_f32 v[138:139], v[230:231], v[234:235], v[138:139] op_sel_hi:[0,1,1]
	v_pk_fma_f32 v[136:137], v[230:231], v[224:225], v[136:137] op_sel_hi:[0,1,1]
	v_pk_fma_f32 v[224:225], v[230:231], v[238:239], v[130:131] op_sel_hi:[0,1,1]
	v_mul_f32_e32 v130, v143, v143
	v_mul_f32_e32 v131, v145, v145
	v_pk_mul_f32 v[222:223], v[100:101], v[222:223]
	v_pk_mul_f32 v[226:227], v[84:85], v[226:227]
	v_pk_fma_f32 v[220:221], v[230:231], v[236:237], v[134:135] op_sel_hi:[0,1,1]
	v_mul_f32_e32 v134, v139, v139
	v_fmac_f32_e32 v130, v142, v142
	v_fmac_f32_e32 v131, v144, v144
	v_pk_fma_f32 v[140:141], v[230:231], v[222:223], v[140:141] op_sel_hi:[0,1,1]
	v_pk_fma_f32 v[222:223], v[230:231], v[226:227], v[132:133] op_sel_hi:[0,1,1]
	v_cvt_pk_bf16_f32 v132, v142, v143
	v_cvt_pk_bf16_f32 v133, v144, v145
	v_mul_f32_e32 v143, v221, v221
	v_mul_f32_e32 v145, v137, v137
	v_fmac_f32_e32 v134, v138, v138
	v_add_f32_e32 v130, v130, v131
	v_fmac_f32_e32 v143, v220, v220
	v_fmac_f32_e32 v145, v136, v136
	v_add_f32_e32 v130, v134, v130
	v_mul_f32_e32 v134, v225, v225
	v_add_f32_e32 v131, v143, v145
	v_fmac_f32_e32 v134, v224, v224
	v_mul_f32_e32 v135, v141, v141
	v_add_f32_e32 v131, v134, v131
	v_mul_f32_e32 v134, v223, v223
	v_fmac_f32_e32 v135, v140, v140
	v_fmac_f32_e32 v134, v222, v222
	v_add_f32_e32 v130, v135, v130
	v_add_f32_e32 v131, v134, v131
	v_and_b32_e32 v134, 64, v211
	v_add_f32_e32 v131, v130, v131
	v_xor_b32_e32 v130, 16, v211
	v_add_u32_e32 v142, 64, v134
	v_cmp_lt_i32_e32 vcc, v130, v142
	v_cvt_pk_bf16_f32 v134, v138, v139
	v_cvt_pk_bf16_f32 v135, v140, v141
	global_store_dwordx4 v[228:229], v[132:135], off
	s_nop 0
	v_cndmask_b32_e32 v130, v211, v130, vcc
	v_lshlrev_b32_e32 v130, 2, v130
	v_mov_b32_e32 v143, v131
	s_nop 1
	v_permlane16_swap_b32_e32 v143, v131
	s_nop 1
	v_cvt_pk_bf16_f32 v134, v220, v221
	v_cvt_pk_bf16_f32 v135, v136, v137
	v_cvt_pk_bf16_f32 v136, v224, v225
	v_cvt_pk_bf16_f32 v137, v222, v223
	s_waitcnt lgkmcnt(0)
	v_add_f32_e32 v132, v131, v143
	v_xor_b32_e32 v131, 32, v211
	v_cmp_lt_i32_e32 vcc, v131, v142
	global_store_dwordx4 v[228:229], v[134:137], off offset:256
	s_nop 0
	v_cndmask_b32_e32 v131, v211, v131, vcc
	v_lshlrev_b32_e32 v131, 2, v131
	v_mov_b32_e32 v133, v132
	s_nop 1
	v_permlane32_swap_b32_e32 v133, v132
	s_nop 1
	s_and_saveexec_b64 s[26:27], s[4:5]
	s_cbranch_execz .LBB0_520
	v_lshl_add_u64 v[134:135], v[198:199], 2, s[60:61]
	s_waitcnt lgkmcnt(0)
	v_add_f32_e32 v132, v132, v133
	global_atomic_add_f32 v[134:135], v132, off
.LBB0_520:
	s_or_b64 exec, exec, s[26:27]
	v_lshlrev_b32_e32 v134, 16, v166
	v_and_b32_e32 v135, 0xffff0000, v166
	v_lshlrev_b32_e32 v136, 16, v167
	v_and_b32_e32 v137, 0xffff0000, v167
	v_pk_mul_f32 v[134:135], v[102:103], v[134:135]
	v_lshlrev_b32_e32 v138, 16, v168
	v_and_b32_e32 v139, 0xffff0000, v168
	v_lshlrev_b32_e32 v140, 16, v169
	v_and_b32_e32 v141, 0xffff0000, v169
	v_pk_mul_f32 v[136:137], v[104:105], v[136:137]
	v_pk_mul_f32 v[138:139], v[98:99], v[138:139]
	v_pk_mul_f32 v[140:141], v[100:101], v[140:141]
	v_pk_fma_f32 v[126:127], v[216:217], v[134:135], v[126:127] op_sel_hi:[0,1,1]
	v_pk_fma_f32 v[128:129], v[216:217], v[136:137], v[128:129] op_sel_hi:[0,1,1]
	v_pk_fma_f32 v[134:135], v[216:217], v[140:141], v[124:125] op_sel_hi:[0,1,1]
	v_pk_fma_f32 v[124:125], v[216:217], v[138:139], v[122:123] op_sel_hi:[0,1,1]
	v_cvt_pk_bf16_f32 v122, v126, v127
	v_mul_f32_e32 v127, v127, v127
	v_fmac_f32_e32 v127, v126, v126
	v_mul_f32_e32 v126, v129, v129
	v_fmac_f32_e32 v126, v128, v128
	v_add_f32_e32 v126, v127, v126
	v_mul_f32_e32 v127, v125, v125
	v_fmac_f32_e32 v127, v124, v124
	v_add_f32_e32 v126, v127, v126
	v_mul_f32_e32 v127, v135, v135
	v_fmac_f32_e32 v127, v134, v134
	v_cvt_pk_bf16_f32 v123, v128, v129
	v_add_f32_e32 v140, v127, v126
	v_lshlrev_b32_e32 v126, 16, v162
	v_and_b32_e32 v127, 0xffff0000, v162
	v_lshlrev_b32_e32 v128, 16, v163
	v_and_b32_e32 v129, 0xffff0000, v163
	v_pk_mul_f32 v[126:127], v[86:87], v[126:127]
	v_pk_mul_f32 v[128:129], v[88:89], v[128:129]
	v_lshlrev_b32_e32 v136, 16, v164
	v_and_b32_e32 v137, 0xffff0000, v164
	v_pk_mul_f32 v[136:137], v[82:83], v[136:137]
	v_pk_fma_f32 v[120:121], v[216:217], v[128:129], v[120:121] op_sel_hi:[0,1,1]
	v_pk_fma_f32 v[118:119], v[216:217], v[126:127], v[118:119] op_sel_hi:[0,1,1]
	v_pk_fma_f32 v[128:129], v[216:217], v[136:137], v[114:115] op_sel_hi:[0,1,1]
	v_mul_f32_e32 v114, v119, v119
	v_mul_f32_e32 v115, v121, v121
	v_lshlrev_b32_e32 v138, 16, v165
	v_and_b32_e32 v139, 0xffff0000, v165
	v_fmac_f32_e32 v114, v118, v118
	v_fmac_f32_e32 v115, v120, v120
	v_pk_mul_f32 v[138:139], v[84:85], v[138:139]
	v_add_f32_e32 v114, v114, v115
	v_mul_f32_e32 v115, v129, v129
	v_pk_fma_f32 v[126:127], v[216:217], v[138:139], v[116:117] op_sel_hi:[0,1,1]
	v_fmac_f32_e32 v115, v128, v128
	v_add_f32_e32 v114, v115, v114
	v_mul_f32_e32 v115, v127, v127
	v_fmac_f32_e32 v115, v126, v126
	v_add_f32_e32 v114, v115, v114
	v_add_f32_e32 v114, v140, v114
	v_mov_b32_e32 v115, v114
	s_nop 1
	v_permlane16_swap_b32_e32 v115, v114
	s_nop 1
	s_waitcnt lgkmcnt(1)
	v_lshl_add_u64 v[132:133], s[40:41], 0, v[218:219]
	v_lshl_add_u64 v[132:133], v[190:191], 1, v[132:133]
	v_cvt_pk_bf16_f32 v124, v124, v125
	v_cvt_pk_bf16_f32 v125, v134, v135
	s_waitcnt lgkmcnt(0)
	v_add_f32_e32 v114, v114, v115
	v_mov_b32_e32 v115, v114
	s_nop 1
	v_permlane32_swap_b32_e32 v115, v114
	s_nop 1
	global_store_dwordx4 v[132:133], v[122:125], off
	v_cvt_pk_bf16_f32 v116, v118, v119
	v_cvt_pk_bf16_f32 v117, v120, v121
	v_cvt_pk_bf16_f32 v118, v128, v129
	v_cvt_pk_bf16_f32 v119, v126, v127
	global_store_dwordx4 v[132:133], v[116:119], off offset:256
	s_and_saveexec_b64 s[26:27], s[4:5]
	s_cbranch_execz .LBB0_522
	v_lshl_add_u64 v[116:117], v[212:213], 2, s[60:61]
	s_waitcnt lgkmcnt(0)
	v_add_f32_e32 v114, v114, v115
	global_atomic_add_f32 v[116:117], v114, off
.LBB0_522:
	s_or_b64 exec, exec, s[26:27]
	v_lshlrev_b32_e32 v116, 16, v158
	v_and_b32_e32 v117, 0xffff0000, v158
	v_lshlrev_b32_e32 v118, 16, v159
	v_and_b32_e32 v119, 0xffff0000, v159
	v_pk_mul_f32 v[116:117], v[102:103], v[116:117]
	v_lshlrev_b32_e32 v120, 16, v160
	v_and_b32_e32 v121, 0xffff0000, v160
	v_lshlrev_b32_e32 v122, 16, v161
	v_and_b32_e32 v123, 0xffff0000, v161
	v_pk_mul_f32 v[118:119], v[104:105], v[118:119]
	v_pk_mul_f32 v[120:121], v[98:99], v[120:121]
	v_pk_mul_f32 v[122:123], v[100:101], v[122:123]
	v_pk_fma_f32 v[110:111], v[210:211], v[116:117], v[110:111] op_sel_hi:[0,1,1]
	v_pk_fma_f32 v[112:113], v[210:211], v[118:119], v[112:113] op_sel_hi:[0,1,1]
	v_pk_fma_f32 v[116:117], v[210:211], v[122:123], v[108:109] op_sel_hi:[0,1,1]
	v_pk_fma_f32 v[108:109], v[210:211], v[120:121], v[106:107] op_sel_hi:[0,1,1]
	v_cvt_pk_bf16_f32 v106, v110, v111
	v_mul_f32_e32 v111, v111, v111
	v_fmac_f32_e32 v111, v110, v110
	v_mul_f32_e32 v110, v113, v113
	v_fmac_f32_e32 v110, v112, v112
	v_add_f32_e32 v110, v111, v110
	v_mul_f32_e32 v111, v109, v109
	v_fmac_f32_e32 v111, v108, v108
	v_add_f32_e32 v110, v111, v110
	v_mul_f32_e32 v111, v117, v117
	v_fmac_f32_e32 v111, v116, v116
	v_cvt_pk_bf16_f32 v107, v112, v113
	v_add_f32_e32 v122, v111, v110
	v_lshlrev_b32_e32 v110, 16, v154
	v_and_b32_e32 v111, 0xffff0000, v154
	v_lshlrev_b32_e32 v112, 16, v155
	v_and_b32_e32 v113, 0xffff0000, v155
	v_pk_mul_f32 v[110:111], v[86:87], v[110:111]
	v_pk_mul_f32 v[112:113], v[88:89], v[112:113]
	v_lshlrev_b32_e32 v118, 16, v156
	v_and_b32_e32 v119, 0xffff0000, v156
	v_pk_mul_f32 v[118:119], v[82:83], v[118:119]
	v_pk_fma_f32 v[96:97], v[210:211], v[112:113], v[96:97] op_sel_hi:[0,1,1]
	v_pk_fma_f32 v[94:95], v[210:211], v[110:111], v[94:95] op_sel_hi:[0,1,1]
	v_pk_fma_f32 v[112:113], v[210:211], v[118:119], v[90:91] op_sel_hi:[0,1,1]
	v_mul_f32_e32 v90, v95, v95
	v_mul_f32_e32 v91, v97, v97
	v_lshlrev_b32_e32 v120, 16, v157
	v_and_b32_e32 v121, 0xffff0000, v157
	v_fmac_f32_e32 v90, v94, v94
	v_fmac_f32_e32 v91, v96, v96
	v_pk_mul_f32 v[120:121], v[84:85], v[120:121]
	v_add_f32_e32 v90, v90, v91
	v_mul_f32_e32 v91, v113, v113
	v_pk_fma_f32 v[110:111], v[210:211], v[120:121], v[92:93] op_sel_hi:[0,1,1]
	v_fmac_f32_e32 v91, v112, v112
	v_add_f32_e32 v90, v91, v90
	v_mul_f32_e32 v91, v111, v111
	v_fmac_f32_e32 v91, v110, v110
	v_add_f32_e32 v90, v91, v90
	v_add_f32_e32 v90, v122, v90
	v_mov_b32_e32 v91, v90
	s_nop 1
	v_permlane16_swap_b32_e32 v91, v90
	s_nop 1
	s_waitcnt lgkmcnt(1)
	v_lshl_add_u64 v[114:115], s[40:41], 0, v[214:215]
	v_lshl_add_u64 v[114:115], v[190:191], 1, v[114:115]
	v_cvt_pk_bf16_f32 v108, v108, v109
	v_cvt_pk_bf16_f32 v109, v116, v117
	s_waitcnt lgkmcnt(0)
	v_add_f32_e32 v90, v90, v91
	v_mov_b32_e32 v91, v90
	s_nop 1
	v_permlane32_swap_b32_e32 v91, v90
	s_nop 1
	global_store_dwordx4 v[114:115], v[106:109], off
	v_cvt_pk_bf16_f32 v92, v94, v95
	v_cvt_pk_bf16_f32 v93, v96, v97
	v_cvt_pk_bf16_f32 v94, v112, v113
	v_cvt_pk_bf16_f32 v95, v110, v111
	global_store_dwordx4 v[114:115], v[92:95], off offset:256
	s_and_saveexec_b64 s[26:27], s[4:5]
	s_cbranch_execz .LBB0_524
	v_lshl_add_u64 v[92:93], v[206:207], 2, s[60:61]
	s_waitcnt lgkmcnt(0)
	v_add_f32_e32 v90, v90, v91
	global_atomic_add_f32 v[92:93], v90, off
.LBB0_524:
	s_or_b64 exec, exec, s[26:27]
	v_lshlrev_b32_e32 v92, 16, v150
	v_and_b32_e32 v93, 0xffff0000, v150
	v_lshlrev_b32_e32 v94, 16, v151
	v_and_b32_e32 v95, 0xffff0000, v151
	v_pk_mul_f32 v[92:93], v[102:103], v[92:93]
	v_lshlrev_b32_e32 v96, 16, v152
	v_and_b32_e32 v97, 0xffff0000, v152
	v_lshlrev_b32_e32 v106, 16, v153
	v_and_b32_e32 v107, 0xffff0000, v153
	v_pk_mul_f32 v[94:95], v[104:105], v[94:95]
	v_pk_mul_f32 v[96:97], v[98:99], v[96:97]
	v_pk_mul_f32 v[106:107], v[100:101], v[106:107]
	v_pk_fma_f32 v[78:79], v[204:205], v[92:93], v[78:79] op_sel_hi:[0,1,1]
	v_pk_fma_f32 v[80:81], v[204:205], v[94:95], v[80:81] op_sel_hi:[0,1,1]
	v_pk_fma_f32 v[92:93], v[204:205], v[106:107], v[76:77] op_sel_hi:[0,1,1]
	v_pk_fma_f32 v[76:77], v[204:205], v[96:97], v[74:75] op_sel_hi:[0,1,1]
	v_cvt_pk_bf16_f32 v74, v78, v79
	v_mul_f32_e32 v79, v79, v79
	v_fmac_f32_e32 v79, v78, v78
	v_mul_f32_e32 v78, v81, v81
	v_fmac_f32_e32 v78, v80, v80
	v_add_f32_e32 v78, v79, v78
	v_mul_f32_e32 v79, v77, v77
	v_fmac_f32_e32 v79, v76, v76
	v_add_f32_e32 v78, v79, v78
	v_mul_f32_e32 v79, v93, v93
	v_fmac_f32_e32 v79, v92, v92
	v_cvt_pk_bf16_f32 v75, v80, v81
	v_add_f32_e32 v106, v79, v78
	v_lshlrev_b32_e32 v78, 16, v146
	v_and_b32_e32 v79, 0xffff0000, v146
	v_lshlrev_b32_e32 v80, 16, v147
	v_and_b32_e32 v81, 0xffff0000, v147
	v_pk_mul_f32 v[78:79], v[86:87], v[78:79]
	v_pk_mul_f32 v[80:81], v[88:89], v[80:81]
	v_lshlrev_b32_e32 v94, 16, v148
	v_and_b32_e32 v95, 0xffff0000, v148
	v_pk_mul_f32 v[94:95], v[82:83], v[94:95]
	v_pk_fma_f32 v[72:73], v[204:205], v[80:81], v[72:73] op_sel_hi:[0,1,1]
	v_pk_fma_f32 v[70:71], v[204:205], v[78:79], v[70:71] op_sel_hi:[0,1,1]
	v_pk_fma_f32 v[80:81], v[204:205], v[94:95], v[66:67] op_sel_hi:[0,1,1]
	v_mul_f32_e32 v66, v71, v71
	v_mul_f32_e32 v67, v73, v73
	v_lshlrev_b32_e32 v96, 16, v149
	v_and_b32_e32 v97, 0xffff0000, v149
	v_fmac_f32_e32 v66, v70, v70
	v_fmac_f32_e32 v67, v72, v72
	v_pk_mul_f32 v[96:97], v[84:85], v[96:97]
	v_add_f32_e32 v66, v66, v67
	v_mul_f32_e32 v67, v81, v81
	v_pk_fma_f32 v[78:79], v[204:205], v[96:97], v[68:69] op_sel_hi:[0,1,1]
	v_fmac_f32_e32 v67, v80, v80
	v_add_f32_e32 v66, v67, v66
	v_mul_f32_e32 v67, v79, v79
	v_fmac_f32_e32 v67, v78, v78
	v_add_f32_e32 v66, v67, v66
	v_add_f32_e32 v66, v106, v66
	v_mov_b32_e32 v67, v66
	s_nop 1
	v_permlane16_swap_b32_e32 v67, v66
	s_nop 1
	s_waitcnt lgkmcnt(1)
	v_lshl_add_u64 v[90:91], s[40:41], 0, v[208:209]
	v_lshl_add_u64 v[90:91], v[190:191], 1, v[90:91]
	v_cvt_pk_bf16_f32 v76, v76, v77
	v_cvt_pk_bf16_f32 v77, v92, v93
	s_waitcnt lgkmcnt(0)
	v_add_f32_e32 v66, v66, v67
	v_mov_b32_e32 v67, v66
	s_nop 1
	v_permlane32_swap_b32_e32 v67, v66
	s_nop 1
	global_store_dwordx4 v[90:91], v[74:77], off
	v_cvt_pk_bf16_f32 v68, v70, v71
	v_cvt_pk_bf16_f32 v69, v72, v73
	v_cvt_pk_bf16_f32 v70, v80, v81
	v_cvt_pk_bf16_f32 v71, v78, v79
	global_store_dwordx4 v[90:91], v[68:71], off offset:256
	s_and_saveexec_b64 s[26:27], s[4:5]
	s_cbranch_execz .LBB0_526
	v_lshl_add_u64 v[68:69], v[202:203], 2, s[60:61]
	s_waitcnt lgkmcnt(0)
	v_add_f32_e32 v66, v66, v67
	global_atomic_add_f32 v[68:69], v66, off
.LBB0_526:
	s_or_b64 exec, exec, s[26:27]
	v_add_u32_e32 v116, 0x80, v198
	v_ashrrev_i32_e32 v117, 31, v116
	v_lshlrev_b64 v[128:129], 11, v[116:117]
	s_waitcnt lgkmcnt(0)
	v_lshl_add_u64 v[66:67], v[200:201], 0, v[128:129]
	global_load_dwordx4 v[120:123], v[66:67], off
	global_load_dwordx4 v[124:127], v[66:67], off offset:256
	v_add_u32_e32 v112, 0x90, v198
	v_add_u32_e32 v108, 0xa0, v198
	v_add_u32_e32 v106, 0xb0, v198
	v_ashrrev_i32_e32 v113, 31, v112
	v_ashrrev_i32_e32 v109, 31, v108
	v_ashrrev_i32_e32 v107, 31, v106
	v_lshlrev_b64 v[118:119], 11, v[112:113]
	v_lshlrev_b64 v[114:115], 11, v[108:109]
	v_lshlrev_b64 v[110:111], 11, v[106:107]
	v_lshl_add_u64 v[66:67], v[200:201], 0, v[118:119]
	v_lshl_add_u64 v[68:69], v[200:201], 0, v[114:115]
	v_lshl_add_u64 v[132:133], v[200:201], 0, v[110:111]
	global_load_dwordx4 v[94:97], v[66:67], off
	global_load_dwordx4 v[90:93], v[66:67], off offset:256
	global_load_dwordx4 v[78:81], v[68:69], off
	global_load_dwordx4 v[74:77], v[68:69], off offset:256
	global_load_dwordx4 v[70:73], v[132:133], off
	s_nop 0
	global_load_dwordx4 v[66:69], v[132:133], off offset:256
	v_lshl_add_u64 v[128:129], s[40:41], 0, v[128:129]
	v_lshl_add_u64 v[128:129], v[190:191], 1, v[128:129]
	s_waitcnt vmcnt(7)
	v_lshlrev_b32_e32 v132, 16, v120
	v_and_b32_e32 v133, 0xffff0000, v120
	v_lshlrev_b32_e32 v120, 16, v121
	v_and_b32_e32 v121, 0xffff0000, v121
	s_waitcnt vmcnt(6)
	v_lshlrev_b32_e32 v136, 16, v124
	v_and_b32_e32 v137, 0xffff0000, v124
	v_lshlrev_b32_e32 v124, 16, v125
	v_and_b32_e32 v125, 0xffff0000, v125
	v_lshlrev_b32_e32 v134, 16, v122
	v_and_b32_e32 v135, 0xffff0000, v122
	v_lshlrev_b32_e32 v122, 16, v123
	v_and_b32_e32 v123, 0xffff0000, v123
	v_lshlrev_b32_e32 v138, 16, v126
	v_and_b32_e32 v139, 0xffff0000, v126
	v_lshlrev_b32_e32 v126, 16, v127
	v_and_b32_e32 v127, 0xffff0000, v127
	v_pk_mul_f32 v[132:133], v[102:103], v[132:133]
	v_pk_mul_f32 v[120:121], v[104:105], v[120:121]
	v_pk_mul_f32 v[136:137], v[86:87], v[136:137]
	v_pk_mul_f32 v[124:125], v[88:89], v[124:125]
	v_pk_mul_f32 v[134:135], v[98:99], v[134:135]
	v_pk_mul_f32 v[122:123], v[100:101], v[122:123]
	v_pk_mul_f32 v[138:139], v[82:83], v[138:139]
	v_pk_mul_f32 v[126:127], v[84:85], v[126:127]
	v_pk_fma_f32 v[64:65], v[196:197], v[120:121], v[64:65] op_sel_hi:[0,1,1]
	v_pk_fma_f32 v[62:63], v[196:197], v[132:133], v[62:63] op_sel_hi:[0,1,1]
	v_pk_fma_f32 v[56:57], v[196:197], v[124:125], v[56:57] op_sel_hi:[0,1,1]
	v_pk_fma_f32 v[54:55], v[196:197], v[136:137], v[54:55] op_sel_hi:[0,1,1]
	v_pk_fma_f32 v[60:61], v[196:197], v[122:123], v[60:61] op_sel_hi:[0,1,1]
	v_pk_fma_f32 v[58:59], v[196:197], v[134:135], v[58:59] op_sel_hi:[0,1,1]
	v_pk_fma_f32 v[120:121], v[196:197], v[126:127], v[52:53] op_sel_hi:[0,1,1]
	v_pk_fma_f32 v[122:123], v[196:197], v[138:139], v[50:51] op_sel_hi:[0,1,1]
	v_mul_f32_e32 v52, v63, v63
	v_mul_f32_e32 v53, v65, v65
	v_mul_f32_e32 v124, v55, v55
	v_mul_f32_e32 v125, v57, v57
	v_cvt_pk_bf16_f32 v50, v62, v63
	v_mul_f32_e32 v63, v59, v59
	v_mul_f32_e32 v126, v123, v123
	v_fmac_f32_e32 v52, v62, v62
	v_fmac_f32_e32 v53, v64, v64
	v_fmac_f32_e32 v124, v54, v54
	v_fmac_f32_e32 v125, v56, v56
	v_cvt_pk_bf16_f32 v51, v64, v65
	v_mul_f32_e32 v65, v61, v61
	v_mul_f32_e32 v127, v121, v121
	v_fmac_f32_e32 v63, v58, v58
	v_fmac_f32_e32 v126, v122, v122
	v_add_f32_e32 v52, v52, v53
	v_add_f32_e32 v53, v124, v125
	v_fmac_f32_e32 v65, v60, v60
	v_fmac_f32_e32 v127, v120, v120
	v_add_f32_e32 v52, v63, v52
	v_add_f32_e32 v53, v126, v53
	v_add_f32_e32 v52, v65, v52
	v_add_f32_e32 v53, v127, v53
	v_add_f32_e32 v62, v52, v53
	v_mov_b32_e32 v63, v62
	s_nop 1
	v_permlane16_swap_b32_e32 v63, v62
	s_nop 1
	v_cvt_pk_bf16_f32 v52, v58, v59
	v_cvt_pk_bf16_f32 v53, v60, v61
	global_store_dwordx4 v[128:129], v[50:53], off
	s_waitcnt lgkmcnt(0)
	s_nop 0
	v_add_f32_e32 v50, v62, v63
	v_mov_b32_e32 v51, v50
	s_nop 1
	v_permlane32_swap_b32_e32 v51, v50
	s_nop 1
	v_cvt_pk_bf16_f32 v52, v54, v55
	v_cvt_pk_bf16_f32 v53, v56, v57
	v_cvt_pk_bf16_f32 v54, v122, v123
	v_cvt_pk_bf16_f32 v55, v120, v121
	global_store_dwordx4 v[128:129], v[52:55], off offset:256
	s_and_saveexec_b64 s[26:27], s[4:5]
	s_cbranch_execz .LBB0_528
	v_lshl_add_u64 v[52:53], v[116:117], 2, s[60:61]
	s_waitcnt lgkmcnt(0)
	v_add_f32_e32 v50, v50, v51
	global_atomic_add_f32 v[52:53], v50, off
.LBB0_528:
	s_or_b64 exec, exec, s[26:27]
	s_waitcnt vmcnt(7)
	v_lshlrev_b32_e32 v52, 16, v94
	v_and_b32_e32 v53, 0xffff0000, v94
	v_lshlrev_b32_e32 v54, 16, v95
	v_and_b32_e32 v55, 0xffff0000, v95
	v_pk_mul_f32 v[52:53], v[102:103], v[52:53]
	v_lshlrev_b32_e32 v56, 16, v96
	v_and_b32_e32 v57, 0xffff0000, v96
	v_lshlrev_b32_e32 v58, 16, v97
	v_and_b32_e32 v59, 0xffff0000, v97
	v_pk_mul_f32 v[54:55], v[104:105], v[54:55]
	v_pk_mul_f32 v[56:57], v[98:99], v[56:57]
	v_pk_mul_f32 v[58:59], v[100:101], v[58:59]
	v_pk_fma_f32 v[46:47], v[194:195], v[52:53], v[46:47] op_sel_hi:[0,1,1]
	v_pk_fma_f32 v[48:49], v[194:195], v[54:55], v[48:49] op_sel_hi:[0,1,1]
	v_pk_fma_f32 v[52:53], v[194:195], v[58:59], v[44:45] op_sel_hi:[0,1,1]
	v_pk_fma_f32 v[44:45], v[194:195], v[56:57], v[42:43] op_sel_hi:[0,1,1]
	v_cvt_pk_bf16_f32 v42, v46, v47
	v_mul_f32_e32 v47, v47, v47
	v_fmac_f32_e32 v47, v46, v46
	v_mul_f32_e32 v46, v49, v49
	v_fmac_f32_e32 v46, v48, v48
	v_add_f32_e32 v46, v47, v46
	v_mul_f32_e32 v47, v45, v45
	v_fmac_f32_e32 v47, v44, v44
	v_add_f32_e32 v46, v47, v46
	v_mul_f32_e32 v47, v53, v53
	v_fmac_f32_e32 v47, v52, v52
	v_cvt_pk_bf16_f32 v43, v48, v49
	v_add_f32_e32 v58, v47, v46
	s_waitcnt vmcnt(6)
	v_lshlrev_b32_e32 v46, 16, v90
	v_and_b32_e32 v47, 0xffff0000, v90
	v_lshlrev_b32_e32 v48, 16, v91
	v_and_b32_e32 v49, 0xffff0000, v91
	v_pk_mul_f32 v[46:47], v[86:87], v[46:47]
	v_pk_mul_f32 v[48:49], v[88:89], v[48:49]
	v_lshlrev_b32_e32 v54, 16, v92
	v_and_b32_e32 v55, 0xffff0000, v92
	v_pk_mul_f32 v[54:55], v[82:83], v[54:55]
	v_pk_fma_f32 v[40:41], v[194:195], v[48:49], v[40:41] op_sel_hi:[0,1,1]
	v_pk_fma_f32 v[38:39], v[194:195], v[46:47], v[38:39] op_sel_hi:[0,1,1]
	v_pk_fma_f32 v[48:49], v[194:195], v[54:55], v[34:35] op_sel_hi:[0,1,1]
	v_mul_f32_e32 v34, v39, v39
	v_mul_f32_e32 v35, v41, v41
	v_lshlrev_b32_e32 v56, 16, v93
	v_and_b32_e32 v57, 0xffff0000, v93
	v_fmac_f32_e32 v34, v38, v38
	v_fmac_f32_e32 v35, v40, v40
	v_pk_mul_f32 v[56:57], v[84:85], v[56:57]
	v_add_f32_e32 v34, v34, v35
	v_mul_f32_e32 v35, v49, v49
	v_pk_fma_f32 v[46:47], v[194:195], v[56:57], v[36:37] op_sel_hi:[0,1,1]
	v_fmac_f32_e32 v35, v48, v48
	v_add_f32_e32 v34, v35, v34
	v_mul_f32_e32 v35, v47, v47
	v_fmac_f32_e32 v35, v46, v46
	v_add_f32_e32 v34, v35, v34
	v_add_f32_e32 v34, v58, v34
	v_mov_b32_e32 v35, v34
	s_nop 1
	v_permlane16_swap_b32_e32 v35, v34
	s_nop 1
	s_waitcnt lgkmcnt(1)
	v_lshl_add_u64 v[50:51], s[40:41], 0, v[118:119]
	v_lshl_add_u64 v[50:51], v[190:191], 1, v[50:51]
	v_cvt_pk_bf16_f32 v44, v44, v45
	v_cvt_pk_bf16_f32 v45, v52, v53
	s_waitcnt lgkmcnt(0)
	v_add_f32_e32 v34, v34, v35
	v_mov_b32_e32 v35, v34
	s_nop 1
	v_permlane32_swap_b32_e32 v35, v34
	s_nop 1
	global_store_dwordx4 v[50:51], v[42:45], off
	v_cvt_pk_bf16_f32 v36, v38, v39
	v_cvt_pk_bf16_f32 v37, v40, v41
	v_cvt_pk_bf16_f32 v38, v48, v49
	v_cvt_pk_bf16_f32 v39, v46, v47
	global_store_dwordx4 v[50:51], v[36:39], off offset:256
	s_and_saveexec_b64 s[26:27], s[4:5]
	s_cbranch_execz .LBB0_530
	v_lshl_add_u64 v[36:37], v[112:113], 2, s[60:61]
	s_waitcnt lgkmcnt(0)
	v_add_f32_e32 v34, v34, v35
	global_atomic_add_f32 v[36:37], v34, off
.LBB0_530:
	s_or_b64 exec, exec, s[26:27]
	s_waitcnt vmcnt(7)
	v_lshlrev_b32_e32 v36, 16, v78
	v_and_b32_e32 v37, 0xffff0000, v78
	v_lshlrev_b32_e32 v38, 16, v79
	v_and_b32_e32 v39, 0xffff0000, v79
	v_pk_mul_f32 v[36:37], v[102:103], v[36:37]
	v_lshlrev_b32_e32 v40, 16, v80
	v_and_b32_e32 v41, 0xffff0000, v80
	v_lshlrev_b32_e32 v42, 16, v81
	v_and_b32_e32 v43, 0xffff0000, v81
	v_pk_mul_f32 v[38:39], v[104:105], v[38:39]
	v_pk_mul_f32 v[40:41], v[98:99], v[40:41]
	v_pk_mul_f32 v[42:43], v[100:101], v[42:43]
	v_pk_fma_f32 v[30:31], v[192:193], v[36:37], v[30:31] op_sel_hi:[0,1,1]
	v_pk_fma_f32 v[32:33], v[192:193], v[38:39], v[32:33] op_sel_hi:[0,1,1]
	v_pk_fma_f32 v[36:37], v[192:193], v[42:43], v[28:29] op_sel_hi:[0,1,1]
	v_pk_fma_f32 v[28:29], v[192:193], v[40:41], v[26:27] op_sel_hi:[0,1,1]
	v_cvt_pk_bf16_f32 v26, v30, v31
	v_mul_f32_e32 v31, v31, v31
	v_fmac_f32_e32 v31, v30, v30
	v_mul_f32_e32 v30, v33, v33
	v_fmac_f32_e32 v30, v32, v32
	v_add_f32_e32 v30, v31, v30
	v_mul_f32_e32 v31, v29, v29
	v_fmac_f32_e32 v31, v28, v28
	v_add_f32_e32 v30, v31, v30
	v_mul_f32_e32 v31, v37, v37
	v_fmac_f32_e32 v31, v36, v36
	v_cvt_pk_bf16_f32 v27, v32, v33
	v_add_f32_e32 v42, v31, v30
	s_waitcnt vmcnt(6)
	v_lshlrev_b32_e32 v30, 16, v74
	v_and_b32_e32 v31, 0xffff0000, v74
	v_lshlrev_b32_e32 v32, 16, v75
	v_and_b32_e32 v33, 0xffff0000, v75
	v_pk_mul_f32 v[30:31], v[86:87], v[30:31]
	v_pk_mul_f32 v[32:33], v[88:89], v[32:33]
	v_lshlrev_b32_e32 v38, 16, v76
	v_and_b32_e32 v39, 0xffff0000, v76
	v_pk_mul_f32 v[38:39], v[82:83], v[38:39]
	v_pk_fma_f32 v[24:25], v[192:193], v[32:33], v[24:25] op_sel_hi:[0,1,1]
	v_pk_fma_f32 v[22:23], v[192:193], v[30:31], v[22:23] op_sel_hi:[0,1,1]
	v_pk_fma_f32 v[32:33], v[192:193], v[38:39], v[18:19] op_sel_hi:[0,1,1]
	v_mul_f32_e32 v18, v23, v23
	v_mul_f32_e32 v19, v25, v25
	v_lshlrev_b32_e32 v40, 16, v77
	v_and_b32_e32 v41, 0xffff0000, v77
	v_fmac_f32_e32 v18, v22, v22
	v_fmac_f32_e32 v19, v24, v24
	v_pk_mul_f32 v[40:41], v[84:85], v[40:41]
	v_add_f32_e32 v18, v18, v19
	v_mul_f32_e32 v19, v33, v33
	v_pk_fma_f32 v[30:31], v[192:193], v[40:41], v[20:21] op_sel_hi:[0,1,1]
	v_fmac_f32_e32 v19, v32, v32
	v_add_f32_e32 v18, v19, v18
	v_mul_f32_e32 v19, v31, v31
	v_fmac_f32_e32 v19, v30, v30
	v_add_f32_e32 v18, v19, v18
	v_add_f32_e32 v18, v42, v18
	v_mov_b32_e32 v19, v18
	s_nop 1
	v_permlane16_swap_b32_e32 v19, v18
	s_nop 1
	s_waitcnt lgkmcnt(1)
	v_lshl_add_u64 v[34:35], s[40:41], 0, v[114:115]
	v_lshl_add_u64 v[34:35], v[190:191], 1, v[34:35]
	v_cvt_pk_bf16_f32 v28, v28, v29
	v_cvt_pk_bf16_f32 v29, v36, v37
	s_waitcnt lgkmcnt(0)
	v_add_f32_e32 v18, v18, v19
	v_mov_b32_e32 v19, v18
	s_nop 1
	v_permlane32_swap_b32_e32 v19, v18
	s_nop 1
	global_store_dwordx4 v[34:35], v[26:29], off
	v_cvt_pk_bf16_f32 v20, v22, v23
	v_cvt_pk_bf16_f32 v21, v24, v25
	v_cvt_pk_bf16_f32 v22, v32, v33
	v_cvt_pk_bf16_f32 v23, v30, v31
	global_store_dwordx4 v[34:35], v[20:23], off offset:256
	s_and_saveexec_b64 s[26:27], s[4:5]
	s_cbranch_execz .LBB0_532
	v_lshl_add_u64 v[20:21], v[108:109], 2, s[60:61]
	s_waitcnt lgkmcnt(0)
	v_add_f32_e32 v18, v18, v19
	global_atomic_add_f32 v[20:21], v18, off
.LBB0_532:
	s_or_b64 exec, exec, s[26:27]
	s_waitcnt vmcnt(7)
	v_lshlrev_b32_e32 v20, 16, v70
	v_and_b32_e32 v21, 0xffff0000, v70
	v_lshlrev_b32_e32 v22, 16, v71
	v_and_b32_e32 v23, 0xffff0000, v71
	v_pk_mul_f32 v[20:21], v[102:103], v[20:21]
	v_lshlrev_b32_e32 v24, 16, v72
	v_and_b32_e32 v25, 0xffff0000, v72
	v_lshlrev_b32_e32 v26, 16, v73
	v_and_b32_e32 v27, 0xffff0000, v73
	v_pk_mul_f32 v[22:23], v[104:105], v[22:23]
	v_pk_mul_f32 v[24:25], v[98:99], v[24:25]
	v_pk_mul_f32 v[26:27], v[100:101], v[26:27]
	v_pk_fma_f32 v[14:15], v[188:189], v[20:21], v[14:15] op_sel_hi:[0,1,1]
	v_pk_fma_f32 v[16:17], v[188:189], v[22:23], v[16:17] op_sel_hi:[0,1,1]
	v_pk_fma_f32 v[20:21], v[188:189], v[26:27], v[12:13] op_sel_hi:[0,1,1]
	v_pk_fma_f32 v[12:13], v[188:189], v[24:25], v[10:11] op_sel_hi:[0,1,1]
	v_cvt_pk_bf16_f32 v10, v14, v15
	v_mul_f32_e32 v15, v15, v15
	v_fmac_f32_e32 v15, v14, v14
	v_mul_f32_e32 v14, v17, v17
	v_fmac_f32_e32 v14, v16, v16
	v_add_f32_e32 v14, v15, v14
	v_mul_f32_e32 v15, v13, v13
	v_fmac_f32_e32 v15, v12, v12
	v_add_f32_e32 v14, v15, v14
	v_mul_f32_e32 v15, v21, v21
	v_fmac_f32_e32 v15, v20, v20
	v_cvt_pk_bf16_f32 v11, v16, v17
	v_add_f32_e32 v26, v15, v14
	s_waitcnt vmcnt(6)
	v_lshlrev_b32_e32 v14, 16, v66
	v_and_b32_e32 v15, 0xffff0000, v66
	v_lshlrev_b32_e32 v16, 16, v67
	v_and_b32_e32 v17, 0xffff0000, v67
	v_pk_mul_f32 v[14:15], v[86:87], v[14:15]
	v_pk_mul_f32 v[16:17], v[88:89], v[16:17]
	v_lshlrev_b32_e32 v22, 16, v68
	v_and_b32_e32 v23, 0xffff0000, v68
	v_pk_mul_f32 v[22:23], v[82:83], v[22:23]
	v_pk_fma_f32 v[8:9], v[188:189], v[16:17], v[8:9] op_sel_hi:[0,1,1]
	v_pk_fma_f32 v[6:7], v[188:189], v[14:15], v[6:7] op_sel_hi:[0,1,1]
	v_pk_fma_f32 v[16:17], v[188:189], v[22:23], v[2:3] op_sel_hi:[0,1,1]
	v_mul_f32_e32 v2, v7, v7
	v_mul_f32_e32 v3, v9, v9
	v_lshlrev_b32_e32 v24, 16, v69
	v_and_b32_e32 v25, 0xffff0000, v69
	v_fmac_f32_e32 v2, v6, v6
	v_fmac_f32_e32 v3, v8, v8
	v_pk_mul_f32 v[24:25], v[84:85], v[24:25]
	v_add_f32_e32 v2, v2, v3
	v_mul_f32_e32 v3, v17, v17
	v_pk_fma_f32 v[14:15], v[188:189], v[24:25], v[4:5] op_sel_hi:[0,1,1]
	v_fmac_f32_e32 v3, v16, v16
	v_add_f32_e32 v2, v3, v2
	v_mul_f32_e32 v3, v15, v15
	v_fmac_f32_e32 v3, v14, v14
	v_add_f32_e32 v2, v3, v2
	v_add_f32_e32 v2, v26, v2
	v_mov_b32_e32 v3, v2
	s_nop 1
	v_permlane16_swap_b32_e32 v3, v2
	s_nop 1
	s_waitcnt lgkmcnt(1)
	v_lshl_add_u64 v[18:19], s[40:41], 0, v[110:111]
	v_lshl_add_u64 v[18:19], v[190:191], 1, v[18:19]
	v_cvt_pk_bf16_f32 v12, v12, v13
	v_cvt_pk_bf16_f32 v13, v20, v21
	s_waitcnt lgkmcnt(0)
	v_add_f32_e32 v2, v2, v3
	v_mov_b32_e32 v3, v2
	s_nop 1
	v_permlane32_swap_b32_e32 v3, v2
	s_nop 1
	global_store_dwordx4 v[18:19], v[10:13], off
	v_cvt_pk_bf16_f32 v4, v6, v7
	v_cvt_pk_bf16_f32 v5, v8, v9
	v_cvt_pk_bf16_f32 v6, v16, v17
	v_cvt_pk_bf16_f32 v7, v14, v15
	global_store_dwordx4 v[18:19], v[4:7], off offset:256
	s_and_saveexec_b64 s[26:27], s[4:5]
	s_cbranch_execz .LBB0_534
	v_lshl_add_u64 v[4:5], v[106:107], 2, s[60:61]
	s_waitcnt lgkmcnt(0)
	v_add_f32_e32 v2, v2, v3
	global_atomic_add_f32 v[4:5], v2, off

.LBB0_702:
	s_andn2_b64 vcc, exec, s[50:51]
	s_cbranch_vccnz .LBB0_740
	v_lshlrev_b32_e32 v130, 1, v182
	v_lshl_add_u32 v170, v180, 11, v130
	v_or_b32_e32 v188, 0x100, v170
	global_load_dwordx4 v[190:193], v170, s[40:41]
	global_load_dwordx4 v[194:197], v188, s[40:41]
	v_add_u32_e32 v186, 0x8000, v170
	v_add_u32_e32 v184, 0x8100, v170
	v_add_u32_e32 v160, 0x10000, v170
	v_add_u32_e32 v158, 0x10100, v170
	v_add_u32_e32 v156, 0x18000, v170
	v_add_u32_e32 v154, 0x18100, v170
	global_load_dwordx4 v[150:153], v186, s[40:41]
	global_load_dwordx4 v[146:149], v184, s[40:41]
	global_load_dwordx4 v[142:145], v160, s[40:41]
	global_load_dwordx4 v[138:141], v158, s[40:41]
	global_load_dwordx4 v[134:137], v156, s[40:41]
	global_load_dwordx4 v[130:133], v154, s[40:41]
	v_and_b32_e32 v157, 64, v211
	v_xor_b32_e32 v155, 16, v211
	v_add_u32_e32 v157, 64, v157
	v_cmp_lt_i32_e32 vcc, v155, v157
	s_waitcnt vmcnt(0)
	v_lshlrev_b32_e32 v198, 16, v190
	v_and_b32_e32 v199, 0xffff0000, v190
	v_lshlrev_b32_e32 v190, 16, v191
	v_and_b32_e32 v191, 0xffff0000, v191
	v_lshlrev_b32_e32 v202, 16, v194
	v_and_b32_e32 v203, 0xffff0000, v194
	v_lshlrev_b32_e32 v194, 16, v195
	v_and_b32_e32 v195, 0xffff0000, v195
	v_lshlrev_b32_e32 v200, 16, v192
	v_and_b32_e32 v201, 0xffff0000, v192
	v_pk_add_f32 v[128:129], v[128:129], v[190:191]
	v_pk_add_f32 v[126:127], v[126:127], v[198:199]
	v_lshlrev_b32_e32 v204, 16, v196
	v_and_b32_e32 v205, 0xffff0000, v196
	v_pk_add_f32 v[112:113], v[112:113], v[194:195]
	v_pk_add_f32 v[110:111], v[110:111], v[202:203]
	v_lshlrev_b32_e32 v192, 16, v193
	v_and_b32_e32 v193, 0xffff0000, v193
	v_pk_add_f32 v[122:123], v[122:123], v[200:201]
	v_lshlrev_b32_e32 v196, 16, v197
	v_and_b32_e32 v197, 0xffff0000, v197
	v_mul_f32_e32 v159, v127, v127
	v_mul_f32_e32 v161, v129, v129
	v_pk_add_f32 v[106:107], v[106:107], v[204:205]
	v_mul_f32_e32 v185, v111, v111
	v_mul_f32_e32 v187, v113, v113
	v_pk_add_f32 v[124:125], v[124:125], v[192:193]
	v_mul_f32_e32 v181, v123, v123
	v_pk_add_f32 v[108:109], v[108:109], v[196:197]
	v_fmac_f32_e32 v159, v126, v126
	v_fmac_f32_e32 v161, v128, v128
	v_mul_f32_e32 v189, v107, v107
	v_fmac_f32_e32 v185, v110, v110
	v_fmac_f32_e32 v187, v112, v112
	v_mul_f32_e32 v183, v125, v125
	v_fmac_f32_e32 v181, v122, v122
	v_mul_f32_e32 v190, v109, v109
	v_add_f32_e32 v159, v159, v161
	v_fmac_f32_e32 v189, v106, v106
	v_add_f32_e32 v161, v185, v187
	v_fmac_f32_e32 v183, v124, v124
	v_add_f32_e32 v159, v181, v159
	v_add_f32_e32 v161, v189, v161
	v_fmac_f32_e32 v190, v108, v108
	v_cndmask_b32_e32 v155, v211, v155, vcc
	v_add_f32_e32 v159, v183, v159
	v_add_f32_e32 v161, v190, v161
	v_lshlrev_b32_e32 v155, 2, v155
	v_add_f32_e32 v159, v159, v161
	v_mov_b32_e32 v161, v159
	s_nop 1
	v_permlane16_swap_b32_e32 v161, v159
	s_nop 1
	v_xor_b32_e32 v181, 32, v211
	v_cmp_lt_i32_e32 vcc, v181, v157
	s_waitcnt lgkmcnt(0)
	v_add_f32_e32 v159, v159, v161
	v_cndmask_b32_e32 v157, v211, v181, vcc
	v_lshlrev_b32_e32 v157, 2, v157
	v_mov_b32_e32 v161, v159
	s_nop 1
	v_permlane32_swap_b32_e32 v161, v159
	s_nop 1
	s_and_saveexec_b64 s[50:51], s[4:5]
	s_cbranch_execz .LBB0_705
	s_waitcnt lgkmcnt(0)
	v_add_f32_e32 v159, v159, v161
	ds_write_b32 v218, v159
.LBB0_705:
	s_or_b64 exec, exec, s[50:51]
	v_lshlrev_b32_e32 v190, 16, v150
	v_and_b32_e32 v191, 0xffff0000, v150
	v_lshlrev_b32_e32 v150, 16, v151
	v_and_b32_e32 v151, 0xffff0000, v151
	v_pk_add_f32 v[120:121], v[120:121], v[150:151]
	v_pk_add_f32 v[118:119], v[118:119], v[190:191]
	v_lshlrev_b32_e32 v192, 16, v152
	v_and_b32_e32 v193, 0xffff0000, v152
	v_mul_f32_e32 v159, v119, v119
	v_mul_f32_e32 v151, v121, v121
	v_pk_add_f32 v[114:115], v[114:115], v[192:193]
	v_fmac_f32_e32 v159, v118, v118
	v_fmac_f32_e32 v151, v120, v120
	v_lshlrev_b32_e32 v152, 16, v153
	v_and_b32_e32 v153, 0xffff0000, v153
	v_add_f32_e32 v150, v159, v151
	v_mul_f32_e32 v151, v115, v115
	v_pk_add_f32 v[116:117], v[116:117], v[152:153]
	v_fmac_f32_e32 v151, v114, v114
	v_add_f32_e32 v150, v151, v150
	v_mul_f32_e32 v151, v117, v117
	v_fmac_f32_e32 v151, v116, v116
	v_add_f32_e32 v159, v151, v150
	v_lshlrev_b32_e32 v150, 16, v146
	v_and_b32_e32 v151, 0xffff0000, v146
	v_lshlrev_b32_e32 v146, 16, v147
	v_and_b32_e32 v147, 0xffff0000, v147
	v_pk_add_f32 v[96:97], v[96:97], v[146:147]
	v_pk_add_f32 v[94:95], v[94:95], v[150:151]
	v_lshlrev_b32_e32 v152, 16, v148
	v_and_b32_e32 v153, 0xffff0000, v148
	v_mul_f32_e32 v151, v95, v95
	v_mul_f32_e32 v147, v97, v97
	v_pk_add_f32 v[90:91], v[90:91], v[152:153]
	v_fmac_f32_e32 v151, v94, v94
	v_fmac_f32_e32 v147, v96, v96
	v_lshlrev_b32_e32 v148, 16, v149
	v_and_b32_e32 v149, 0xffff0000, v149
	v_add_f32_e32 v146, v151, v147
	v_mul_f32_e32 v147, v91, v91
	v_pk_add_f32 v[92:93], v[92:93], v[148:149]
	v_fmac_f32_e32 v147, v90, v90
	v_add_f32_e32 v146, v147, v146
	v_mul_f32_e32 v147, v93, v93
	v_fmac_f32_e32 v147, v92, v92
	v_add_f32_e32 v146, v147, v146
	v_add_f32_e32 v146, v159, v146
	v_mov_b32_e32 v147, v146
	s_nop 1
	v_permlane16_swap_b32_e32 v147, v146
	s_nop 1
	s_waitcnt lgkmcnt(0)
	v_add_f32_e32 v146, v146, v147
	v_mov_b32_e32 v147, v146
	s_nop 1
	v_permlane32_swap_b32_e32 v147, v146
	s_nop 1
	s_and_saveexec_b64 s[50:51], s[4:5]
	s_cbranch_execz .LBB0_707
	s_waitcnt lgkmcnt(0)
	v_add_f32_e32 v146, v146, v147
	ds_write_b32 v218, v146 offset:256
.LBB0_707:
	s_or_b64 exec, exec, s[50:51]
	v_lshlrev_b32_e32 v146, 16, v142
	s_waitcnt lgkmcnt(0)
	v_and_b32_e32 v147, 0xffff0000, v142
	v_lshlrev_b32_e32 v142, 16, v143
	v_and_b32_e32 v143, 0xffff0000, v143
	v_pk_add_f32 v[104:105], v[104:105], v[142:143]
	v_pk_add_f32 v[102:103], v[102:103], v[146:147]
	v_lshlrev_b32_e32 v148, 16, v144
	v_and_b32_e32 v149, 0xffff0000, v144
	v_mul_f32_e32 v147, v103, v103
	v_mul_f32_e32 v143, v105, v105
	v_pk_add_f32 v[98:99], v[98:99], v[148:149]
	v_fmac_f32_e32 v147, v102, v102
	v_fmac_f32_e32 v143, v104, v104
	v_lshlrev_b32_e32 v144, 16, v145
	v_and_b32_e32 v145, 0xffff0000, v145
	v_add_f32_e32 v142, v147, v143
	v_mul_f32_e32 v143, v99, v99
	v_pk_add_f32 v[100:101], v[100:101], v[144:145]
	v_fmac_f32_e32 v143, v98, v98
	v_add_f32_e32 v142, v143, v142
	v_mul_f32_e32 v143, v101, v101
	v_fmac_f32_e32 v143, v100, v100
	v_add_f32_e32 v146, v143, v142
	v_lshlrev_b32_e32 v142, 16, v138
	v_and_b32_e32 v143, 0xffff0000, v138
	v_lshlrev_b32_e32 v138, 16, v139
	v_and_b32_e32 v139, 0xffff0000, v139
	v_pk_add_f32 v[80:81], v[80:81], v[138:139]
	v_pk_add_f32 v[78:79], v[78:79], v[142:143]
	v_lshlrev_b32_e32 v144, 16, v140
	v_and_b32_e32 v145, 0xffff0000, v140
	v_mul_f32_e32 v143, v79, v79
	v_mul_f32_e32 v139, v81, v81
	v_pk_add_f32 v[74:75], v[74:75], v[144:145]
	v_fmac_f32_e32 v143, v78, v78
	v_fmac_f32_e32 v139, v80, v80
	v_lshlrev_b32_e32 v140, 16, v141
	v_and_b32_e32 v141, 0xffff0000, v141
	v_add_f32_e32 v138, v143, v139
	v_mul_f32_e32 v139, v75, v75
	v_pk_add_f32 v[76:77], v[76:77], v[140:141]
	v_fmac_f32_e32 v139, v74, v74
	v_add_f32_e32 v138, v139, v138
	v_mul_f32_e32 v139, v77, v77
	v_fmac_f32_e32 v139, v76, v76
	v_add_f32_e32 v138, v139, v138
	v_add_f32_e32 v138, v146, v138
	v_mov_b32_e32 v139, v138
	s_nop 1
	v_permlane16_swap_b32_e32 v139, v138
	s_nop 1
	s_waitcnt lgkmcnt(0)
	v_add_f32_e32 v138, v138, v139
	v_mov_b32_e32 v139, v138
	s_nop 1
	v_permlane32_swap_b32_e32 v139, v138
	s_nop 1
	s_and_saveexec_b64 s[50:51], s[4:5]
	s_cbranch_execz .LBB0_709
	s_waitcnt lgkmcnt(0)
	v_add_f32_e32 v138, v138, v139
	ds_write_b32 v218, v138 offset:512
.LBB0_709:
	s_or_b64 exec, exec, s[50:51]
	v_lshlrev_b32_e32 v138, 16, v134
	s_waitcnt lgkmcnt(0)
	v_and_b32_e32 v139, 0xffff0000, v134
	v_lshlrev_b32_e32 v134, 16, v135
	v_and_b32_e32 v135, 0xffff0000, v135
	v_pk_add_f32 v[88:89], v[88:89], v[134:135]
	v_pk_add_f32 v[86:87], v[86:87], v[138:139]
	v_lshlrev_b32_e32 v140, 16, v136
	v_and_b32_e32 v141, 0xffff0000, v136
	v_mul_f32_e32 v139, v87, v87
	v_mul_f32_e32 v135, v89, v89
	v_pk_add_f32 v[82:83], v[82:83], v[140:141]
	v_fmac_f32_e32 v139, v86, v86
	v_fmac_f32_e32 v135, v88, v88
	v_lshlrev_b32_e32 v136, 16, v137
	v_and_b32_e32 v137, 0xffff0000, v137
	v_add_f32_e32 v134, v139, v135
	v_mul_f32_e32 v135, v83, v83
	v_pk_add_f32 v[84:85], v[84:85], v[136:137]
	v_fmac_f32_e32 v135, v82, v82
	v_add_f32_e32 v134, v135, v134
	v_mul_f32_e32 v135, v85, v85
	v_fmac_f32_e32 v135, v84, v84
	v_add_f32_e32 v138, v135, v134
	v_lshlrev_b32_e32 v134, 16, v130
	v_and_b32_e32 v135, 0xffff0000, v130
	v_lshlrev_b32_e32 v130, 16, v131
	v_and_b32_e32 v131, 0xffff0000, v131
	v_pk_add_f32 v[72:73], v[72:73], v[130:131]
	v_pk_add_f32 v[70:71], v[70:71], v[134:135]
	v_lshlrev_b32_e32 v136, 16, v132
	v_and_b32_e32 v137, 0xffff0000, v132
	v_mul_f32_e32 v135, v71, v71
	v_mul_f32_e32 v131, v73, v73
	v_pk_add_f32 v[66:67], v[66:67], v[136:137]
	v_fmac_f32_e32 v135, v70, v70
	v_fmac_f32_e32 v131, v72, v72
	v_lshlrev_b32_e32 v132, 16, v133
	v_and_b32_e32 v133, 0xffff0000, v133
	v_add_f32_e32 v130, v135, v131
	v_mul_f32_e32 v131, v67, v67
	v_pk_add_f32 v[68:69], v[68:69], v[132:133]
	v_fmac_f32_e32 v131, v66, v66
	v_add_f32_e32 v130, v131, v130
	v_mul_f32_e32 v131, v69, v69
	v_fmac_f32_e32 v131, v68, v68
	v_add_f32_e32 v130, v131, v130
	v_add_f32_e32 v130, v138, v130
	v_mov_b32_e32 v131, v130
	s_nop 1
	v_permlane16_swap_b32_e32 v131, v130
	s_nop 1
	s_waitcnt lgkmcnt(0)
	v_add_f32_e32 v130, v130, v131
	v_mov_b32_e32 v131, v130
	s_nop 1
	v_permlane32_swap_b32_e32 v131, v130
	s_nop 1
	s_and_saveexec_b64 s[50:51], s[4:5]
	s_cbranch_execz .LBB0_711
	s_waitcnt lgkmcnt(0)
	v_add_f32_e32 v130, v130, v131
	ds_write_b32 v218, v130 offset:768
.LBB0_711:
	s_or_b64 exec, exec, s[50:51]
	v_add_u32_e32 v204, 0x40000, v170
	v_add_u32_e32 v202, 0x40100, v170
	global_load_dwordx4 v[220:223], v204, s[40:41]
	global_load_dwordx4 v[224:227], v202, s[40:41]
	v_add_u32_e32 v200, 0x48000, v170
	v_add_u32_e32 v198, 0x48100, v170
	v_add_u32_e32 v196, 0x50000, v170
	v_add_u32_e32 v194, 0x50100, v170
	v_add_u32_e32 v192, 0x58000, v170
	v_add_u32_e32 v190, 0x58100, v170
	global_load_dwordx4 v[150:153], v200, s[40:41]
	global_load_dwordx4 v[146:149], v198, s[40:41]
	global_load_dwordx4 v[142:145], v196, s[40:41]
	global_load_dwordx4 v[138:141], v194, s[40:41]
	global_load_dwordx4 v[134:137], v192, s[40:41]
	s_waitcnt lgkmcnt(0)
	global_load_dwordx4 v[130:133], v190, s[40:41]
	s_waitcnt vmcnt(7)
	v_lshlrev_b32_e32 v206, 16, v220
	v_and_b32_e32 v207, 0xffff0000, v220
	v_lshlrev_b32_e32 v220, 16, v221
	v_and_b32_e32 v221, 0xffff0000, v221
	s_waitcnt vmcnt(6)
	v_lshlrev_b32_e32 v230, 16, v224
	v_and_b32_e32 v231, 0xffff0000, v224
	v_lshlrev_b32_e32 v224, 16, v225
	v_and_b32_e32 v225, 0xffff0000, v225
	v_lshlrev_b32_e32 v228, 16, v222
	v_and_b32_e32 v229, 0xffff0000, v222
	v_lshlrev_b32_e32 v232, 16, v226
	v_and_b32_e32 v233, 0xffff0000, v226
	v_pk_add_f32 v[64:65], v[64:65], v[220:221]
	v_pk_add_f32 v[62:63], v[62:63], v[206:207]
	v_pk_add_f32 v[48:49], v[48:49], v[224:225]
	v_pk_add_f32 v[46:47], v[46:47], v[230:231]
	v_lshlrev_b32_e32 v222, 16, v223
	v_and_b32_e32 v223, 0xffff0000, v223
	v_lshlrev_b32_e32 v226, 16, v227
	v_and_b32_e32 v227, 0xffff0000, v227
	v_pk_add_f32 v[58:59], v[58:59], v[228:229]
	v_pk_add_f32 v[42:43], v[42:43], v[232:233]
	v_mul_f32_e32 v159, v63, v63
	v_mul_f32_e32 v161, v65, v65
	v_mul_f32_e32 v185, v47, v47
	v_mul_f32_e32 v187, v49, v49
	v_pk_add_f32 v[60:61], v[60:61], v[222:223]
	v_pk_add_f32 v[44:45], v[44:45], v[226:227]
	v_mul_f32_e32 v181, v59, v59
	v_mul_f32_e32 v189, v43, v43
	v_fmac_f32_e32 v159, v62, v62
	v_fmac_f32_e32 v161, v64, v64
	v_fmac_f32_e32 v185, v46, v46
	v_fmac_f32_e32 v187, v48, v48
	v_mul_f32_e32 v183, v61, v61
	v_mul_f32_e32 v191, v45, v45
	v_fmac_f32_e32 v181, v58, v58
	v_fmac_f32_e32 v189, v42, v42
	v_add_f32_e32 v159, v159, v161
	v_add_f32_e32 v161, v185, v187
	v_fmac_f32_e32 v183, v60, v60
	v_fmac_f32_e32 v191, v44, v44
	v_add_f32_e32 v159, v181, v159
	v_add_f32_e32 v161, v189, v161
	v_add_f32_e32 v159, v183, v159
	v_add_f32_e32 v161, v191, v161
	v_add_f32_e32 v159, v159, v161
	v_mov_b32_e32 v161, v159
	s_nop 1
	v_permlane16_swap_b32_e32 v161, v159
	s_nop 1
	s_waitcnt lgkmcnt(0)
	v_add_f32_e32 v159, v159, v161
	v_mov_b32_e32 v161, v159
	s_nop 1
	v_permlane32_swap_b32_e32 v161, v159
	s_nop 1
	s_and_saveexec_b64 s[50:51], s[4:5]
	s_cbranch_execz .LBB0_713
	s_waitcnt lgkmcnt(0)
	v_add_f32_e32 v159, v159, v161
	ds_write_b32 v218, v159 offset:2048
.LBB0_713:
	s_or_b64 exec, exec, s[50:51]
	s_waitcnt vmcnt(5)
	v_lshlrev_b32_e32 v206, 16, v150
	v_and_b32_e32 v207, 0xffff0000, v150
	v_lshlrev_b32_e32 v150, 16, v151
	v_and_b32_e32 v151, 0xffff0000, v151
	v_pk_add_f32 v[56:57], v[56:57], v[150:151]
	v_pk_add_f32 v[54:55], v[54:55], v[206:207]
	v_lshlrev_b32_e32 v220, 16, v152
	v_and_b32_e32 v221, 0xffff0000, v152
	v_mul_f32_e32 v159, v55, v55
	v_mul_f32_e32 v151, v57, v57
	v_pk_add_f32 v[50:51], v[50:51], v[220:221]
	v_fmac_f32_e32 v159, v54, v54
	v_fmac_f32_e32 v151, v56, v56
	v_lshlrev_b32_e32 v152, 16, v153
	v_and_b32_e32 v153, 0xffff0000, v153
	v_add_f32_e32 v150, v159, v151
	v_mul_f32_e32 v151, v51, v51
	v_pk_add_f32 v[52:53], v[52:53], v[152:153]
	v_fmac_f32_e32 v151, v50, v50
	v_add_f32_e32 v150, v151, v150
	v_mul_f32_e32 v151, v53, v53
	v_fmac_f32_e32 v151, v52, v52
	v_add_f32_e32 v159, v151, v150
	s_waitcnt vmcnt(4)
	v_lshlrev_b32_e32 v150, 16, v146
	v_and_b32_e32 v151, 0xffff0000, v146
	v_lshlrev_b32_e32 v146, 16, v147
	v_and_b32_e32 v147, 0xffff0000, v147
	v_pk_add_f32 v[32:33], v[32:33], v[146:147]
	v_pk_add_f32 v[30:31], v[30:31], v[150:151]
	v_lshlrev_b32_e32 v152, 16, v148
	v_and_b32_e32 v153, 0xffff0000, v148
	v_mul_f32_e32 v151, v31, v31
	v_mul_f32_e32 v147, v33, v33
	v_pk_add_f32 v[26:27], v[26:27], v[152:153]
	v_fmac_f32_e32 v151, v30, v30
	v_fmac_f32_e32 v147, v32, v32
	v_lshlrev_b32_e32 v148, 16, v149
	v_and_b32_e32 v149, 0xffff0000, v149
	v_add_f32_e32 v146, v151, v147
	v_mul_f32_e32 v147, v27, v27
	v_pk_add_f32 v[28:29], v[28:29], v[148:149]
	v_fmac_f32_e32 v147, v26, v26
	v_add_f32_e32 v146, v147, v146
	v_mul_f32_e32 v147, v29, v29
	v_fmac_f32_e32 v147, v28, v28
	v_add_f32_e32 v146, v147, v146
	v_add_f32_e32 v146, v159, v146
	v_mov_b32_e32 v147, v146
	s_nop 1
	v_permlane16_swap_b32_e32 v147, v146
	s_nop 1
	s_waitcnt lgkmcnt(0)
	v_add_f32_e32 v146, v146, v147
	v_mov_b32_e32 v147, v146
	s_nop 1
	v_permlane32_swap_b32_e32 v147, v146
	s_nop 1
	s_and_saveexec_b64 s[50:51], s[4:5]
	s_cbranch_execz .LBB0_715
	s_waitcnt lgkmcnt(0)
	v_add_f32_e32 v146, v146, v147
	ds_write_b32 v218, v146 offset:2304
.LBB0_715:
	s_or_b64 exec, exec, s[50:51]
	s_waitcnt vmcnt(3)
	v_lshlrev_b32_e32 v146, 16, v142
	s_waitcnt lgkmcnt(0)
	v_and_b32_e32 v147, 0xffff0000, v142
	v_lshlrev_b32_e32 v142, 16, v143
	v_and_b32_e32 v143, 0xffff0000, v143
	v_pk_add_f32 v[40:41], v[40:41], v[142:143]
	v_pk_add_f32 v[38:39], v[38:39], v[146:147]
	v_lshlrev_b32_e32 v148, 16, v144
	v_and_b32_e32 v149, 0xffff0000, v144
	v_mul_f32_e32 v147, v39, v39
	v_mul_f32_e32 v143, v41, v41
	v_pk_add_f32 v[34:35], v[34:35], v[148:149]
	v_fmac_f32_e32 v147, v38, v38
	v_fmac_f32_e32 v143, v40, v40
	v_lshlrev_b32_e32 v144, 16, v145
	v_and_b32_e32 v145, 0xffff0000, v145
	v_add_f32_e32 v142, v147, v143
	v_mul_f32_e32 v143, v35, v35
	v_pk_add_f32 v[36:37], v[36:37], v[144:145]
	v_fmac_f32_e32 v143, v34, v34
	v_add_f32_e32 v142, v143, v142
	v_mul_f32_e32 v143, v37, v37
	v_fmac_f32_e32 v143, v36, v36
	v_add_f32_e32 v146, v143, v142
	s_waitcnt vmcnt(2)
	v_lshlrev_b32_e32 v142, 16, v138
	v_and_b32_e32 v143, 0xffff0000, v138
	v_lshlrev_b32_e32 v138, 16, v139
	v_and_b32_e32 v139, 0xffff0000, v139
	v_pk_add_f32 v[16:17], v[16:17], v[138:139]
	v_pk_add_f32 v[14:15], v[14:15], v[142:143]
	v_lshlrev_b32_e32 v144, 16, v140
	v_and_b32_e32 v145, 0xffff0000, v140
	v_mul_f32_e32 v143, v15, v15
	v_mul_f32_e32 v139, v17, v17
	v_pk_add_f32 v[10:11], v[10:11], v[144:145]
	v_fmac_f32_e32 v143, v14, v14
	v_fmac_f32_e32 v139, v16, v16
	v_lshlrev_b32_e32 v140, 16, v141
	v_and_b32_e32 v141, 0xffff0000, v141
	v_add_f32_e32 v138, v143, v139
	v_mul_f32_e32 v139, v11, v11
	v_pk_add_f32 v[12:13], v[12:13], v[140:141]
	v_fmac_f32_e32 v139, v10, v10
	v_add_f32_e32 v138, v139, v138
	v_mul_f32_e32 v139, v13, v13
	v_fmac_f32_e32 v139, v12, v12
	v_add_f32_e32 v138, v139, v138
	v_add_f32_e32 v138, v146, v138
	v_mov_b32_e32 v139, v138
	s_nop 1
	v_permlane16_swap_b32_e32 v139, v138
	s_nop 1
	s_waitcnt lgkmcnt(0)
	v_add_f32_e32 v138, v138, v139
	v_mov_b32_e32 v139, v138
	s_nop 1
	v_permlane32_swap_b32_e32 v139, v138
	s_nop 1
	s_and_saveexec_b64 s[50:51], s[4:5]
	s_cbranch_execz .LBB0_717
	s_waitcnt lgkmcnt(0)
	v_add_f32_e32 v138, v138, v139
	ds_write_b32 v218, v138 offset:2560
.LBB0_717:
	s_or_b64 exec, exec, s[50:51]
	s_waitcnt vmcnt(1)
	v_lshlrev_b32_e32 v138, 16, v134
	s_waitcnt lgkmcnt(0)
	v_and_b32_e32 v139, 0xffff0000, v134
	v_lshlrev_b32_e32 v134, 16, v135
	v_and_b32_e32 v135, 0xffff0000, v135
	v_pk_add_f32 v[24:25], v[24:25], v[134:135]
	v_pk_add_f32 v[22:23], v[22:23], v[138:139]
	v_lshlrev_b32_e32 v140, 16, v136
	v_and_b32_e32 v141, 0xffff0000, v136
	v_mul_f32_e32 v139, v23, v23
	v_mul_f32_e32 v135, v25, v25
	v_pk_add_f32 v[18:19], v[18:19], v[140:141]
	v_fmac_f32_e32 v139, v22, v22
	v_fmac_f32_e32 v135, v24, v24
	v_lshlrev_b32_e32 v136, 16, v137
	v_and_b32_e32 v137, 0xffff0000, v137
	v_add_f32_e32 v134, v139, v135
	v_mul_f32_e32 v135, v19, v19
	v_pk_add_f32 v[20:21], v[20:21], v[136:137]
	v_fmac_f32_e32 v135, v18, v18
	v_add_f32_e32 v134, v135, v134
	v_mul_f32_e32 v135, v21, v21
	v_fmac_f32_e32 v135, v20, v20
	v_add_f32_e32 v138, v135, v134
	s_waitcnt vmcnt(0)
	v_lshlrev_b32_e32 v134, 16, v130
	v_and_b32_e32 v135, 0xffff0000, v130
	v_lshlrev_b32_e32 v130, 16, v131
	v_and_b32_e32 v131, 0xffff0000, v131
	v_pk_add_f32 v[8:9], v[8:9], v[130:131]
	v_pk_add_f32 v[6:7], v[6:7], v[134:135]
	v_lshlrev_b32_e32 v136, 16, v132
	v_and_b32_e32 v137, 0xffff0000, v132
	v_mul_f32_e32 v135, v7, v7
	v_mul_f32_e32 v131, v9, v9
	v_pk_add_f32 v[2:3], v[2:3], v[136:137]
	v_fmac_f32_e32 v135, v6, v6
	v_fmac_f32_e32 v131, v8, v8
	v_lshlrev_b32_e32 v132, 16, v133
	v_and_b32_e32 v133, 0xffff0000, v133
	v_add_f32_e32 v130, v135, v131
	v_mul_f32_e32 v131, v3, v3
	v_pk_add_f32 v[4:5], v[4:5], v[132:133]
	v_fmac_f32_e32 v131, v2, v2
	v_add_f32_e32 v130, v131, v130
	v_mul_f32_e32 v131, v5, v5
	v_fmac_f32_e32 v131, v4, v4
	v_add_f32_e32 v130, v131, v130
	v_add_f32_e32 v130, v138, v130
	v_mov_b32_e32 v131, v130
	s_nop 1
	v_permlane16_swap_b32_e32 v131, v130
	s_nop 1
	s_waitcnt lgkmcnt(0)
	v_add_f32_e32 v130, v130, v131
	v_mov_b32_e32 v131, v130
	s_nop 1
	v_permlane32_swap_b32_e32 v131, v130
	s_nop 1
	s_and_saveexec_b64 s[50:51], s[4:5]
	s_cbranch_execz .LBB0_719
	s_waitcnt lgkmcnt(0)
	v_add_f32_e32 v130, v130, v131
	ds_write_b32 v218, v130 offset:2816
